# v46: prep phase: adaLN GEMV with 32 weight loads in flight, weight-copy items re-dealt (one 4KiB-pitch out-projection block per wave, 2/3/7 in-projection blocks by workgroup class); final RMSNorm gain
# speedup vs baseline: 1.7450x; 1.0012x over previous
.LBB0_6:
	v_lshl_add_u64 v[40:41], v[8:9], 0, s[28:29]
	global_load_dword v56, v[40:41], off
	s_add_u32 s28, s28, 0x3000
	s_addc_u32 s29, s29, 0
	v_lshl_add_u64 v[40:41], v[8:9], 0, s[28:29]
	global_load_dword v57, v[40:41], off
	s_add_u32 s28, s28, 0x3000
	s_addc_u32 s29, s29, 0
	v_lshl_add_u64 v[40:41], v[8:9], 0, s[28:29]
	global_load_dword v58, v[40:41], off
	s_add_u32 s28, s28, 0x3000
	s_addc_u32 s29, s29, 0
	v_lshl_add_u64 v[40:41], v[8:9], 0, s[28:29]
	global_load_dword v59, v[40:41], off
	s_add_u32 s28, s28, 0x3000
	s_addc_u32 s29, s29, 0
	v_lshl_add_u64 v[40:41], v[8:9], 0, s[28:29]
	global_load_dword v60, v[40:41], off
	s_add_u32 s28, s28, 0x3000
	s_addc_u32 s29, s29, 0
	v_lshl_add_u64 v[40:41], v[8:9], 0, s[28:29]
	global_load_dword v61, v[40:41], off
	s_add_u32 s28, s28, 0x3000
	s_addc_u32 s29, s29, 0
	v_lshl_add_u64 v[40:41], v[8:9], 0, s[28:29]
	global_load_dword v62, v[40:41], off
	s_add_u32 s28, s28, 0x3000
	s_addc_u32 s29, s29, 0
	v_lshl_add_u64 v[40:41], v[8:9], 0, s[28:29]
	global_load_dword v63, v[40:41], off
	s_add_u32 s28, s28, 0x3000
	s_addc_u32 s29, s29, 0
	v_lshl_add_u64 v[40:41], v[8:9], 0, s[28:29]
	global_load_dword v64, v[40:41], off
	s_add_u32 s28, s28, 0x3000
	s_addc_u32 s29, s29, 0
	v_lshl_add_u64 v[40:41], v[8:9], 0, s[28:29]
	global_load_dword v65, v[40:41], off
	s_add_u32 s28, s28, 0x3000
	s_addc_u32 s29, s29, 0
	v_lshl_add_u64 v[40:41], v[8:9], 0, s[28:29]
	global_load_dword v66, v[40:41], off
	s_add_u32 s28, s28, 0x3000
	s_addc_u32 s29, s29, 0
	v_lshl_add_u64 v[40:41], v[8:9], 0, s[28:29]
	global_load_dword v67, v[40:41], off
	s_add_u32 s28, s28, 0x3000
	s_addc_u32 s29, s29, 0
	v_lshl_add_u64 v[40:41], v[8:9], 0, s[28:29]
	global_load_dword v68, v[40:41], off
	s_add_u32 s28, s28, 0x3000
	s_addc_u32 s29, s29, 0
	v_lshl_add_u64 v[40:41], v[8:9], 0, s[28:29]
	global_load_dword v69, v[40:41], off
	s_add_u32 s28, s28, 0x3000
	s_addc_u32 s29, s29, 0
	v_lshl_add_u64 v[40:41], v[8:9], 0, s[28:29]
	global_load_dword v70, v[40:41], off
	s_add_u32 s28, s28, 0x3000
	s_addc_u32 s29, s29, 0
	v_lshl_add_u64 v[40:41], v[8:9], 0, s[28:29]
	global_load_dword v71, v[40:41], off
	s_add_u32 s28, s28, 0x3000
	s_addc_u32 s29, s29, 0
	v_lshl_add_u64 v[40:41], v[8:9], 0, s[28:29]
	global_load_dword v72, v[40:41], off
	s_add_u32 s28, s28, 0x3000
	s_addc_u32 s29, s29, 0
	v_lshl_add_u64 v[40:41], v[8:9], 0, s[28:29]
	global_load_dword v73, v[40:41], off
	s_add_u32 s28, s28, 0x3000
	s_addc_u32 s29, s29, 0
	v_lshl_add_u64 v[40:41], v[8:9], 0, s[28:29]
	global_load_dword v74, v[40:41], off
	s_add_u32 s28, s28, 0x3000
	s_addc_u32 s29, s29, 0
	v_lshl_add_u64 v[40:41], v[8:9], 0, s[28:29]
	global_load_dword v75, v[40:41], off
	s_add_u32 s28, s28, 0x3000
	s_addc_u32 s29, s29, 0
	v_lshl_add_u64 v[40:41], v[8:9], 0, s[28:29]
	global_load_dword v76, v[40:41], off
	s_add_u32 s28, s28, 0x3000
	s_addc_u32 s29, s29, 0
	v_lshl_add_u64 v[40:41], v[8:9], 0, s[28:29]
	global_load_dword v77, v[40:41], off
	s_add_u32 s28, s28, 0x3000
	s_addc_u32 s29, s29, 0
	v_lshl_add_u64 v[40:41], v[8:9], 0, s[28:29]
	global_load_dword v78, v[40:41], off
	s_add_u32 s28, s28, 0x3000
	s_addc_u32 s29, s29, 0
	v_lshl_add_u64 v[40:41], v[8:9], 0, s[28:29]
	global_load_dword v79, v[40:41], off
	s_add_u32 s28, s28, 0x3000
	s_addc_u32 s29, s29, 0
	v_lshl_add_u64 v[40:41], v[8:9], 0, s[28:29]
	global_load_dword v80, v[40:41], off
	s_add_u32 s28, s28, 0x3000
	s_addc_u32 s29, s29, 0
	v_lshl_add_u64 v[40:41], v[8:9], 0, s[28:29]
	global_load_dword v81, v[40:41], off
	s_add_u32 s28, s28, 0x3000
	s_addc_u32 s29, s29, 0
	v_lshl_add_u64 v[40:41], v[8:9], 0, s[28:29]
	global_load_dword v82, v[40:41], off
	s_add_u32 s28, s28, 0x3000
	s_addc_u32 s29, s29, 0
	v_lshl_add_u64 v[40:41], v[8:9], 0, s[28:29]
	global_load_dword v83, v[40:41], off
	s_add_u32 s28, s28, 0x3000
	s_addc_u32 s29, s29, 0
	v_lshl_add_u64 v[40:41], v[8:9], 0, s[28:29]
	global_load_dword v84, v[40:41], off
	s_add_u32 s28, s28, 0x3000
	s_addc_u32 s29, s29, 0
	v_lshl_add_u64 v[40:41], v[8:9], 0, s[28:29]
	global_load_dword v85, v[40:41], off
	s_add_u32 s28, s28, 0x3000
	s_addc_u32 s29, s29, 0
	v_lshl_add_u64 v[40:41], v[8:9], 0, s[28:29]
	global_load_dword v86, v[40:41], off
	s_add_u32 s28, s28, 0x3000
	s_addc_u32 s29, s29, 0
	v_lshl_add_u64 v[40:41], v[8:9], 0, s[28:29]
	global_load_dword v87, v[40:41], off
	s_add_u32 s28, s28, 0x3000
	s_addc_u32 s29, s29, 0
	ds_read_b128 v[14:17], v13
	ds_read_b128 v[18:21], v13 offset:16
	ds_read_b128 v[22:25], v13 offset:4096
	ds_read_b128 v[26:29], v13 offset:4112
	ds_read_b128 v[30:33], v13 offset:8192
	ds_read_b128 v[34:37], v13 offset:8208
	v_add_u32_e32 v13, 32, v13
	s_waitcnt lgkmcnt(0)
	s_waitcnt vmcnt(31)
	v_fmac_f32_e32 v10, v56, v14
	v_fmac_f32_e32 v11, v56, v22
	v_fmac_f32_e32 v12, v56, v30
	s_waitcnt vmcnt(30)
	v_fmac_f32_e32 v10, v57, v15
	v_fmac_f32_e32 v11, v57, v23
	v_fmac_f32_e32 v12, v57, v31
	s_waitcnt vmcnt(29)
	v_fmac_f32_e32 v10, v58, v16
	v_fmac_f32_e32 v11, v58, v24
	v_fmac_f32_e32 v12, v58, v32
	s_waitcnt vmcnt(28)
	v_fmac_f32_e32 v10, v59, v17
	v_fmac_f32_e32 v11, v59, v25
	v_fmac_f32_e32 v12, v59, v33
	s_waitcnt vmcnt(27)
	v_fmac_f32_e32 v10, v60, v18
	v_fmac_f32_e32 v11, v60, v26
	v_fmac_f32_e32 v12, v60, v34
	s_waitcnt vmcnt(26)
	v_fmac_f32_e32 v10, v61, v19
	v_fmac_f32_e32 v11, v61, v27
	v_fmac_f32_e32 v12, v61, v35
	s_waitcnt vmcnt(25)
	v_fmac_f32_e32 v10, v62, v20
	v_fmac_f32_e32 v11, v62, v28
	v_fmac_f32_e32 v12, v62, v36
	s_waitcnt vmcnt(24)
	v_fmac_f32_e32 v10, v63, v21
	v_fmac_f32_e32 v11, v63, v29
	v_fmac_f32_e32 v12, v63, v37
	ds_read_b128 v[14:17], v13
	ds_read_b128 v[18:21], v13 offset:16
	ds_read_b128 v[22:25], v13 offset:4096
	ds_read_b128 v[26:29], v13 offset:4112
	ds_read_b128 v[30:33], v13 offset:8192
	ds_read_b128 v[34:37], v13 offset:8208
	v_add_u32_e32 v13, 32, v13
	s_waitcnt lgkmcnt(0)
	s_waitcnt vmcnt(23)
	v_fmac_f32_e32 v10, v64, v14
	v_fmac_f32_e32 v11, v64, v22
	v_fmac_f32_e32 v12, v64, v30
	s_waitcnt vmcnt(22)
	v_fmac_f32_e32 v10, v65, v15
	v_fmac_f32_e32 v11, v65, v23
	v_fmac_f32_e32 v12, v65, v31
	s_waitcnt vmcnt(21)
	v_fmac_f32_e32 v10, v66, v16
	v_fmac_f32_e32 v11, v66, v24
	v_fmac_f32_e32 v12, v66, v32
	s_waitcnt vmcnt(20)
	v_fmac_f32_e32 v10, v67, v17
	v_fmac_f32_e32 v11, v67, v25
	v_fmac_f32_e32 v12, v67, v33
	s_waitcnt vmcnt(19)
	v_fmac_f32_e32 v10, v68, v18
	v_fmac_f32_e32 v11, v68, v26
	v_fmac_f32_e32 v12, v68, v34
	s_waitcnt vmcnt(18)
	v_fmac_f32_e32 v10, v69, v19
	v_fmac_f32_e32 v11, v69, v27
	v_fmac_f32_e32 v12, v69, v35
	s_waitcnt vmcnt(17)
	v_fmac_f32_e32 v10, v70, v20
	v_fmac_f32_e32 v11, v70, v28
	v_fmac_f32_e32 v12, v70, v36
	s_waitcnt vmcnt(16)
	v_fmac_f32_e32 v10, v71, v21
	v_fmac_f32_e32 v11, v71, v29
	v_fmac_f32_e32 v12, v71, v37
	ds_read_b128 v[14:17], v13
	ds_read_b128 v[18:21], v13 offset:16
	ds_read_b128 v[22:25], v13 offset:4096
	ds_read_b128 v[26:29], v13 offset:4112
	ds_read_b128 v[30:33], v13 offset:8192
	ds_read_b128 v[34:37], v13 offset:8208
	v_add_u32_e32 v13, 32, v13
	s_waitcnt lgkmcnt(0)
	s_waitcnt vmcnt(15)
	v_fmac_f32_e32 v10, v72, v14
	v_fmac_f32_e32 v11, v72, v22
	v_fmac_f32_e32 v12, v72, v30
	s_waitcnt vmcnt(14)
	v_fmac_f32_e32 v10, v73, v15
	v_fmac_f32_e32 v11, v73, v23
	v_fmac_f32_e32 v12, v73, v31
	s_waitcnt vmcnt(13)
	v_fmac_f32_e32 v10, v74, v16
	v_fmac_f32_e32 v11, v74, v24
	v_fmac_f32_e32 v12, v74, v32
	s_waitcnt vmcnt(12)
	v_fmac_f32_e32 v10, v75, v17
	v_fmac_f32_e32 v11, v75, v25
	v_fmac_f32_e32 v12, v75, v33
	s_waitcnt vmcnt(11)
	v_fmac_f32_e32 v10, v76, v18
	v_fmac_f32_e32 v11, v76, v26
	v_fmac_f32_e32 v12, v76, v34
	s_waitcnt vmcnt(10)
	v_fmac_f32_e32 v10, v77, v19
	v_fmac_f32_e32 v11, v77, v27
	v_fmac_f32_e32 v12, v77, v35
	s_waitcnt vmcnt(9)
	v_fmac_f32_e32 v10, v78, v20
	v_fmac_f32_e32 v11, v78, v28
	v_fmac_f32_e32 v12, v78, v36
	s_waitcnt vmcnt(8)
	v_fmac_f32_e32 v10, v79, v21
	v_fmac_f32_e32 v11, v79, v29
	v_fmac_f32_e32 v12, v79, v37
	ds_read_b128 v[14:17], v13
	ds_read_b128 v[18:21], v13 offset:16
	ds_read_b128 v[22:25], v13 offset:4096
	ds_read_b128 v[26:29], v13 offset:4112
	ds_read_b128 v[30:33], v13 offset:8192
	ds_read_b128 v[34:37], v13 offset:8208
	v_add_u32_e32 v13, 32, v13
	s_waitcnt lgkmcnt(0)
	s_waitcnt vmcnt(7)
	v_fmac_f32_e32 v10, v80, v14
	v_fmac_f32_e32 v11, v80, v22
	v_fmac_f32_e32 v12, v80, v30
	s_waitcnt vmcnt(6)
	v_fmac_f32_e32 v10, v81, v15
	v_fmac_f32_e32 v11, v81, v23
	v_fmac_f32_e32 v12, v81, v31
	s_waitcnt vmcnt(5)
	v_fmac_f32_e32 v10, v82, v16
	v_fmac_f32_e32 v11, v82, v24
	v_fmac_f32_e32 v12, v82, v32
	s_waitcnt vmcnt(4)
	v_fmac_f32_e32 v10, v83, v17
	v_fmac_f32_e32 v11, v83, v25
	v_fmac_f32_e32 v12, v83, v33
	s_waitcnt vmcnt(3)
	v_fmac_f32_e32 v10, v84, v18
	v_fmac_f32_e32 v11, v84, v26
	v_fmac_f32_e32 v12, v84, v34
	s_waitcnt vmcnt(2)
	v_fmac_f32_e32 v10, v85, v19
	v_fmac_f32_e32 v11, v85, v27
	v_fmac_f32_e32 v12, v85, v35
	s_waitcnt vmcnt(1)
	v_fmac_f32_e32 v10, v86, v20
	v_fmac_f32_e32 v11, v86, v28
	v_fmac_f32_e32 v12, v86, v36
	s_waitcnt vmcnt(0)
	v_fmac_f32_e32 v10, v87, v21
	v_fmac_f32_e32 v11, v87, v29
	v_fmac_f32_e32 v12, v87, v37
	s_cmp_eq_u32 s28, 0x180000
	s_cbranch_scc0 .LBB0_6
	ds_write2st64_b32 v3, v10, v11 offset0:48 offset1:49
	ds_write_b32 v3, v12 offset:12800
	s_waitcnt lgkmcnt(0)
	s_barrier
	s_and_saveexec_b64 s[4:5], vcc
	s_cbranch_execz .LBB0_4
	s_load_dwordx16 s[36:51], s[0:1], 0x40
	s_mul_i32 s13, s22, 0xc00
	s_add_i32 s13, s13, s12
	v_or_b32_e32 v8, s13, v2
	v_ashrrev_i32_e32 v9, 31, v8
	s_waitcnt lgkmcnt(0)
	v_lshl_add_u64 v[8:9], v[8:9], 2, s[40:41]
	global_load_dword v18, v[8:9], off
	ds_read2st64_b32 v[8:9], v7 offset0:48 offset1:51
	ds_read2st64_b32 v[10:11], v7 offset0:54 offset1:57
	ds_read2st64_b32 v[12:13], v7 offset0:60 offset1:63
	ds_read2st64_b32 v[14:15], v7 offset0:66 offset1:69
	v_mad_u64_u32 v[16:17], s[22:23], s22, 3, v[6:7]
	v_mul_lo_u32 v16, v16, s20
	v_add_u32_e32 v16, s12, v16
	v_or_b32_e32 v16, v16, v2
	v_ashrrev_i32_e32 v17, 31, v16
	s_waitcnt vmcnt(0) lgkmcnt(3)
	v_add_f32_e32 v8, v18, v8
	v_add_f32_e32 v8, v8, v9
	s_waitcnt lgkmcnt(2)
	v_add_f32_e32 v8, v8, v10
	v_add_f32_e32 v8, v8, v11
	s_waitcnt lgkmcnt(1)
	v_add_f32_e32 v8, v8, v12
	v_add_f32_e32 v8, v8, v13
	s_waitcnt lgkmcnt(0)
	v_add_f32_e32 v8, v8, v14
	v_add_f32_e32 v10, v8, v15
	v_lshl_add_u64 v[8:9], v[16:17], 2, s[10:11]
	global_store_dword v[8:9], v10, off
	s_branch .LBB0_4
.LBB0_9:
	s_waitcnt lgkmcnt(0)
	s_cmpk_eq_i32 s3, 0x100
	s_cselect_b64 s[4:5], -1, 0
	s_cmpk_lg_i32 s3, 0x100
	v_lshl_add_u32 v1, s59, 3, v6
	v_writelane_b32 v255, s4, 18
	s_cselect_b64 s[38:39], -1, 0
	s_and_b64 vcc, exec, s[38:39]
	v_writelane_b32 v255, s5, 19
	v_mov_b32_e32 v4, v1
	v_lshrrev_b32_e32 v90, 9, v1
	v_mul_u32_u24_e32 v90, 0x900, v90
	v_and_b32_e32 v91, 0x1ff, v1
	v_add_u32_e32 v90, v90, v91
	v_add_u32_e32 v90, 0x700, v90
	s_cbranch_vccnz .LBB0_14
	s_and_b64 vcc, exec, s[8:9]
	s_cbranch_vccz .LBB0_12
	v_mov_b32_e32 v4, 0xfffff400
	v_mov_b32_e32 v5, -1
	v_mad_u64_u32 v[4:5], s[4:5], v1, 6, v[4:5]
	s_cbranch_execz .LBB0_13
	s_branch .LBB0_14

.LBB0_14:
	v_mul_u32_u24_e32 v91, 3, v1
	v_add_u32_e32 v91, 0xfffffc00, v91
	v_lshlrev_b32_e32 v92, 1, v1
	v_cmp_gt_u32_e32 vcc, 0x400, v1
	s_nop 1
	v_cndmask_b32_e32 v91, v91, v92, vcc
	v_mul_u32_u24_e32 v92, 7, v1
	v_add_u32_e32 v92, 0xffffe400, v92
	v_cmp_lt_u32_e32 vcc, 0x5ff, v1
	s_nop 1
	v_cndmask_b32_e32 v91, v91, v92, vcc
	s_lshl_b32 s28, s3, 3
	s_and_b64 vcc, exec, s[38:39]
	s_cbranch_vccz .LBB0_16
	s_abs_i32 s2, s28
	v_cvt_f32_u32_e32 v3, s2
	v_sub_u32_e32 v1, s28, v1
	v_add_u32_e32 v5, 0x23ff, v1
	v_sub_u32_e32 v1, 0xffffdc01, v1
	v_rcp_iflag_f32_e32 v3, v3
	s_sub_i32 s4, 0, s2
	v_xor_b32_e32 v7, s28, v5
	v_max_i32_e32 v1, v5, v1
	v_mul_f32_e32 v3, 0x4f7ffffe, v3
	v_cvt_u32_f32_e32 v3, v3
	v_ashrrev_i32_e32 v5, 31, v7
	v_mul_lo_u32 v7, s4, v3
	v_mul_hi_u32 v7, v3, v7
	v_add_u32_e32 v3, v3, v7
	v_mul_hi_u32 v3, v1, v3
	v_mul_lo_u32 v7, v3, s2
	v_sub_u32_e32 v1, v1, v7
	v_add_u32_e32 v8, 1, v3
	v_cmp_le_u32_e32 vcc, s2, v1
	v_subrev_u32_e32 v7, s2, v1
	s_mov_b64 s[4:5], 0
	v_cndmask_b32_e32 v3, v3, v8, vcc
	v_cndmask_b32_e32 v1, v1, v7, vcc
	v_add_u32_e32 v7, 1, v3
	v_cmp_le_u32_e32 vcc, s2, v1
	s_nop 1
	v_cndmask_b32_e32 v1, v3, v7, vcc
	v_xor_b32_e32 v1, v1, v5
	v_sub_u32_e32 v5, v1, v5
	s_branch .LBB0_17

.LBB0_17:
	s_load_dwordx8 s[8:15], s[0:1], 0x80
	s_andn2_b64 vcc, exec, s[4:5]
	s_mov_b32 s2, s28
	s_waitcnt lgkmcnt(0)
	v_writelane_b32 v255, s8, 20
	s_nop 1
	v_writelane_b32 v255, s9, 21
	v_writelane_b32 v255, s10, 22
	v_writelane_b32 v255, s11, 23
	v_writelane_b32 v255, s12, 24
	v_writelane_b32 v255, s13, 25
	v_writelane_b32 v255, s14, 26
	v_writelane_b32 v255, s15, 27
	s_cbranch_vccnz .LBB0_19
	s_cmpk_lt_i32 s59, 0x80
	s_cselect_b32 s0, 3, 4
	s_cmpk_gt_i32 s59, 0xbf
	s_cselect_b32 s0, 8, s0
	v_mov_b32_e32 v5, s0
	s_mov_b32 s2, 1

.LBB0_22:
	s_add_i32 s8, s10, -1
	v_add_u32_e32 v3, s8, v91
	v_mov_b32_e32 v13, 0x200
	v_cmp_lt_u32_e32 vcc, 0x6ff, v3
	s_nop 1
	v_cndmask_b32_e32 v8, 0, v13, vcc
	v_cmp_lt_u32_e32 vcc, 0xdff, v3
	s_nop 1
	v_cndmask_b32_e32 v16, 0, v13, vcc
	v_cmp_lt_u32_e32 vcc, 0x14ff, v3
	s_nop 1
	v_cndmask_b32_e32 v17, 0, v13, vcc
	v_add3_u32 v8, v8, v16, v17
	v_add_u32_e32 v3, v3, v8
	s_cmp_eq_u32 s10, 0
	s_cselect_b64 vcc, -1, 0
	v_cndmask_b32_e32 v3, v3, v90, vcc
	v_mul_hi_i32 v8, v3, s12
	v_lshrrev_b32_e32 v13, 31, v8
	v_ashrrev_i32_e32 v8, 9, v8
	v_add_u32_e32 v18, v8, v13
	v_mul_i32_i24_e32 v8, 0x900, v18
	v_sub_u32_e32 v3, v3, v8
	v_cmp_lt_i32_e32 vcc, s13, v3
	v_ashrrev_i32_e32 v19, 31, v18
	s_and_saveexec_b64 s[8:9], vcc
	s_xor_b64 s[8:9], exec, s[8:9]
	s_cbranch_execz .LBB0_26
	v_readlane_b32 s40, v255, 0
	v_lshl_add_u32 v8, v3, 1, v27
	v_lshlrev_b32_e32 v3, 5, v3
	v_lshlrev_b64 v[16:17], 20, v[18:19]
	v_lshlrev_b64 v[18:19], 22, v[18:19]
	v_readlane_b32 s48, v255, 8
	v_readlane_b32 s49, v255, 9
	v_and_b32_e32 v21, 0x3e0, v3
	v_and_b32_e32 v15, 0x1ffc0, v8
	v_lshl_add_u64 v[18:19], s[48:49], 0, v[18:19]
	v_lshlrev_b32_e32 v8, 2, v21
	v_lshl_add_u64 v[18:19], v[18:19], 0, v[8:9]
	v_mov_b32_e32 v13, v9
	s_mov_b32 s16, 1
	v_lshl_add_u64 v[18:19], v[18:19], 0, v[12:13]
	v_or_b32_e32 v3, v1, v15
	v_or_b32_e32 v20, v6, v15
	s_mov_b32 s17, 0
	s_mov_b32 s18, 32
	v_readlane_b32 s41, v255, 1
	v_readlane_b32 s42, v255, 2
	v_readlane_b32 s43, v255, 3
	v_readlane_b32 s44, v255, 4
	v_readlane_b32 s45, v255, 5
	v_readlane_b32 s46, v255, 6
	v_readlane_b32 s47, v255, 7
	v_readlane_b32 s50, v255, 10
	v_readlane_b32 s51, v255, 11
	v_readlane_b32 s52, v255, 12
	v_readlane_b32 s53, v255, 13
	v_readlane_b32 s54, v255, 14
	v_readlane_b32 s55, v255, 15

.LBB0_319:
	s_lshl_b32 s4, s59, 3
	v_ashrrev_i32_e32 v8, 6, v174
	v_add_u32_e32 v0, s4, v8
	s_movk_i32 s0, 0x3000
	v_cmp_gt_i32_e32 vcc, s0, v0
	s_and_saveexec_b64 s[0:1], vcc
	s_cbranch_execz .LBB0_326
	v_lshlrev_b32_e32 v1, 2, v174
	v_cmp_lt_i32_e32 vcc, v183, v177
	v_and_b32_e32 v10, 0xfc, v1
	s_add_u32 s0, s56, 0xa900000
	v_cndmask_b32_e32 v1, v176, v183, vcc
	v_cmp_lt_i32_e32 vcc, v182, v177
	v_lshlrev_b32_e32 v16, 2, v1
	s_addc_u32 s1, s57, 0
	v_cndmask_b32_e32 v1, v176, v182, vcc
	v_cmp_lt_i32_e32 vcc, v179, v177
	v_lshlrev_b32_e32 v17, 2, v1
	v_readlane_b32 s8, v255, 20
	v_cndmask_b32_e32 v1, v176, v179, vcc
	v_cmp_lt_i32_e32 vcc, v254, v177
	v_lshlrev_b32_e32 v18, 2, v1
	s_add_u32 s2, s56, 0xb900000
	v_cndmask_b32_e32 v1, v176, v254, vcc
	v_lshlrev_b32_e32 v19, 2, v1
	v_xor_b32_e32 v1, 16, v176
	v_cmp_lt_i32_e32 vcc, v1, v177
	v_readlane_b32 s9, v255, 21
	v_readlane_b32 s10, v255, 22
	v_readlane_b32 s11, v255, 23
	v_readlane_b32 s12, v255, 24
	v_readlane_b32 s13, v255, 25
	s_addc_u32 s3, s57, 0
	v_cndmask_b32_e32 v1, v176, v1, vcc
	v_cmp_lt_i32_e32 vcc, v178, v177
	v_readlane_b32 s14, v255, 26
	v_readlane_b32 s15, v255, 27
	s_mov_b64 s[8:9], s[12:13]
	v_ashrrev_i32_e32 v9, 31, v8
	s_ashr_i32 s5, s4, 31
	v_lshlrev_b32_e32 v20, 2, v1
	v_cndmask_b32_e32 v1, v176, v178, vcc
	v_mov_b32_e32 v3, 0
	v_lshlrev_b32_e32 v2, 2, v10
	s_mov_b64 s[10:11], s[14:15]
	v_lshl_add_u64 v[8:9], v[8:9], 0, s[4:5]
	v_lshlrev_b32_e32 v21, 2, v1
	v_lshl_add_u64 v[4:5], s[8:9], 0, v[2:3]
	v_lshl_add_u64 v[6:7], s[10:11], 0, v[2:3]
	v_lshlrev_b64 v[8:9], 12, v[8:9]
	s_mov_b64 s[4:5], 0
	s_movk_i32 s8, 0xfff
	v_lshlrev_b32_e32 v10, 2, v10
	v_mov_b32_e32 v11, v3
	v_mov_b32_e32 v22, 0x358637bd
	s_mov_b32 s9, 0x800000
	s_movk_i32 s10, 0x2fff
	global_load_dwordx4 v[56:59], v[4:5], off
	global_load_dwordx4 v[60:63], v[4:5], off offset:1024
	global_load_dwordx4 v[64:67], v[4:5], off offset:2048
	global_load_dwordx4 v[68:71], v[4:5], off offset:3072
	s_branch .LBB0_322
.LBB0_321:
	s_or_b64 exec, exec, s[6:7]
	v_lshl_add_u64 v[14:15], v[14:15], 0, v[10:11]
	global_load_dwordx4 v[24:27], v[14:15], off
	global_load_dwordx4 v[28:31], v[14:15], off offset:1024
	global_load_dwordx4 v[32:35], v[14:15], off offset:3072
	global_load_dwordx4 v[36:39], v[14:15], off offset:2048
	v_add_u32_e32 v0, s28, v0
	v_lshl_add_u64 v[8:9], v[8:9], 0, s[98:99]
	s_waitcnt vmcnt(3)
	v_pk_mul_f32 v[14:15], v[26:27], v[26:27]
	v_pk_mul_f32 v[44:45], v[24:25], v[24:25]
	s_waitcnt vmcnt(2)
	v_pk_mul_f32 v[46:47], v[30:31], v[30:31]
	v_pk_mul_f32 v[48:49], v[28:29], v[28:29]
	v_pk_mov_b32 v[52:53], v[44:45], v[14:15] op_sel:[1,0]
	v_mov_b32_e32 v45, v15
	v_pk_mov_b32 v[14:15], v[48:49], v[46:47] op_sel:[1,0]
	v_mov_b32_e32 v49, v47
	s_waitcnt vmcnt(0)
	v_mul_f32_e32 v2, v37, v37
	v_mul_f32_e32 v50, v39, v39
	v_pk_add_f32 v[44:45], v[52:53], v[44:45]
	v_pk_add_f32 v[14:15], v[14:15], v[48:49]
	v_mul_f32_e32 v1, v32, v32
	v_mul_f32_e32 v23, v33, v33
	v_mul_f32_e32 v54, v34, v34
	v_mul_f32_e32 v55, v35, v35
	v_pk_fma_f32 v[46:47], v[36:37], v[36:37], v[2:3] op_sel_hi:[1,1,0]
	v_pk_fma_f32 v[50:51], v[38:39], v[38:39], v[50:51] op_sel_hi:[1,1,0]
	v_pk_add_f32 v[44:45], v[44:45], v[44:45] op_sel:[0,1] op_sel_hi:[1,0]
	v_pk_add_f32 v[14:15], v[14:15], v[14:15] op_sel:[0,1] op_sel_hi:[1,0]
	v_mov_b32_e32 v47, v54
	v_mov_b32_e32 v51, v55
	v_mov_b32_e32 v45, v1
	v_mov_b32_e32 v15, v23
	v_pk_add_f32 v[46:47], v[46:47], v[50:51]
	v_pk_add_f32 v[14:15], v[44:45], v[14:15]
	v_lshl_add_u64 v[44:45], v[6:7], 0, v[12:13]
	v_pk_add_f32 v[14:15], v[14:15], v[46:47]
	s_nop 0
	v_add_f32_e32 v1, v14, v15
	ds_bpermute_b32 v2, v16, v1
	s_waitcnt lgkmcnt(0)
	v_add_f32_e32 v1, v1, v2
	ds_bpermute_b32 v2, v17, v1
	s_waitcnt lgkmcnt(0)
	v_add_f32_e32 v1, v1, v2
	ds_bpermute_b32 v2, v18, v1
	s_waitcnt lgkmcnt(0)
	v_add_f32_e32 v1, v1, v2
	ds_bpermute_b32 v2, v19, v1
	s_waitcnt lgkmcnt(0)
	v_add_f32_e32 v1, v1, v2
	ds_bpermute_b32 v2, v20, v1
	s_waitcnt lgkmcnt(0)
	v_add_f32_e32 v1, v1, v2
	ds_bpermute_b32 v2, v21, v1
	s_waitcnt lgkmcnt(0)
	v_add_f32_e32 v1, v1, v2
	v_fmamk_f32 v1, v1, 0x3a800000, v22
	v_mul_f32_e32 v2, 0x4b800000, v1
	v_cmp_gt_f32_e32 vcc, s9, v1
	s_nop 1
	v_cndmask_b32_e32 v1, v1, v2, vcc
	v_rsq_f32_e32 v1, v1
	s_nop 0
	v_mul_f32_e32 v2, 0x45800000, v1
	v_cndmask_b32_e32 v2, v1, v2, vcc
	v_pk_mul_f32 v[12:13], v[24:25], v[2:3] op_sel_hi:[1,0]
	v_pk_mul_f32 v[14:15], v[26:27], v[2:3] op_sel_hi:[1,0]
	v_pk_mul_f32 v[12:13], v[56:57], v[12:13]
	v_pk_mul_f32 v[14:15], v[58:59], v[14:15]
	global_store_dwordx4 v[44:45], v[12:15], off
	v_pk_mul_f32 v[24:25], v[30:31], v[2:3] op_sel_hi:[1,0]
	v_pk_mul_f32 v[26:27], v[28:29], v[2:3] op_sel_hi:[1,0]
	v_cmp_lt_i32_e32 vcc, s10, v0
	s_or_b64 s[4:5], vcc, s[4:5]
	v_pk_mul_f32 v[12:13], v[60:61], v[26:27]
	v_pk_mul_f32 v[14:15], v[62:63], v[24:25]
	global_store_dwordx4 v[44:45], v[12:15], off offset:1024
	v_pk_mul_f32 v[24:25], v[38:39], v[2:3] op_sel_hi:[1,0]
	v_pk_mul_f32 v[26:27], v[36:37], v[2:3] op_sel_hi:[1,0]
	s_nop 0
	v_pk_mul_f32 v[14:15], v[66:67], v[24:25]
	v_pk_mul_f32 v[12:13], v[64:65], v[26:27]
	global_store_dwordx4 v[44:45], v[12:15], off offset:2048
	v_pk_mul_f32 v[24:25], v[34:35], v[2:3] op_sel_hi:[1,0]
	v_pk_mul_f32 v[26:27], v[32:33], v[2:3] op_sel_hi:[1,0]
	s_nop 0
	v_pk_mul_f32 v[14:15], v[70:71], v[24:25]
	v_pk_mul_f32 v[12:13], v[68:69], v[26:27]
	global_store_dwordx4 v[44:45], v[12:15], off offset:3072
	s_andn2_b64 exec, exec, s[4:5]
	s_cbranch_execz .LBB0_326
